# PF tiles: rstd loads issued before the main loop into spare registers; epilogue's vmcnt(0) replaced by a counted wait so next-tile LDS-DMA prefetch stays in flight
# baseline (speedup 1.0000x reference)
;     __device__ __forceinline__ void operator()(const f32x4 (&acc)[2][2][4][2], const Unit& u, int wr, int wc, int fr, int fq) const {
;         const int row0 = u.pm * BM + wr * 64 + fr, col0 = u.pn * HALF + wc * 32 + 8 * fq;
;         float rrv[2][4];
; #pragma unroll
;         for (int ai = 0; ai < 2; ++ai)
; #pragma unroll
;             for (int m = 0; m < 4; ++m) rrv[ai][m] = rs[row0 + ai * HALF + m * 16];
; template <class Epi>
; __device__ __forceinline__ void gemm_phase(LAS unsigned char* lds, const Gemm g, const StaticOrder& S, const Epi& E) {
;     ...
;         for (int a = 0; a < 2; ++a)
; #pragma unroll
;             for (int b = 0; b < 2; ++b)
; #pragma unroll
;                 for (int m = 0; m < 4; ++m)
; #pragma unroll
;                     for (int n = 0; n < 2; ++n) acc[a][b][m][n] = (f32x4){0.f, 0.f, 0.f, 0.f};
.LBB0_1549:
	v_lshl_add_u32 v244, s45, 8, v1
	v_ashrrev_i32_e32 v245, 31, v244
	v_lshl_add_u64 v[244:245], v[244:245], 2, s[8:9]
	global_load_dword v236, v[244:245], off
	global_load_dword v237, v[244:245], off offset:64
	global_load_dword v238, v[244:245], off offset:128
	global_load_dword v239, v[244:245], off offset:192
	global_load_dword v240, v[244:245], off offset:512
	global_load_dword v241, v[244:245], off offset:576
	global_load_dword v242, v[244:245], off offset:640
	global_load_dword v243, v[244:245], off offset:704
	s_ashr_i32 s15, s14, 31
	s_lshl_b64 s[16:17], s[14:15], 19
	s_add_u32 s16, s27, s16
	s_addc_u32 s17, s28, s17
	s_and_b64 s[18:19], s[24:25], exec
	s_cselect_b32 s15, s17, s21
	s_cselect_b32 s46, s16, s20
	s_ashr_i32 s13, s12, 31
	s_lshl_b64 s[18:19], s[12:13], 19
	s_add_u32 s18, s29, s18
	s_addc_u32 s19, s30, s19
	s_and_b64 s[24:25], s[24:25], exec
	s_cselect_b32 s13, s19, s23
	s_cselect_b32 s47, s18, s22
	s_add_u32 s20, s20, 0x40080
	s_addc_u32 s21, s21, 0
	s_add_u32 s48, s22, 0x100
	v_mov_b64_e32 v[2:3], 0
	v_mov_b64_e32 v[4:5], 0
	v_mov_b64_e32 v[6:7], 0
	v_mov_b64_e32 v[8:9], 0
	v_mov_b64_e32 v[10:11], 0
	v_mov_b64_e32 v[12:13], 0
	v_mov_b64_e32 v[14:15], 0
	v_mov_b64_e32 v[16:17], 0
	v_mov_b64_e32 v[18:19], 0
	v_mov_b64_e32 v[20:21], 0
	v_mov_b64_e32 v[22:23], 0
	v_mov_b64_e32 v[24:25], 0
	v_mov_b64_e32 v[26:27], 0
	v_mov_b64_e32 v[28:29], 0
	v_mov_b64_e32 v[30:31], 0
	v_mov_b64_e32 v[32:33], 0
	v_mov_b64_e32 v[34:35], 0
	v_mov_b64_e32 v[36:37], 0
	v_mov_b64_e32 v[38:39], 0
	v_mov_b64_e32 v[40:41], 0
	v_mov_b64_e32 v[42:43], 0
	v_mov_b64_e32 v[44:45], 0
	v_mov_b64_e32 v[46:47], 0
	v_mov_b64_e32 v[48:49], 0
	v_mov_b64_e32 v[50:51], 0
	v_mov_b64_e32 v[52:53], 0
	v_mov_b64_e32 v[54:55], 0
	v_mov_b64_e32 v[56:57], 0
	v_mov_b64_e32 v[58:59], 0
	v_mov_b64_e32 v[60:61], 0
	v_mov_b64_e32 v[62:63], 0
	v_mov_b64_e32 v[64:65], 0
	v_mov_b64_e32 v[66:67], 0
	v_mov_b64_e32 v[68:69], 0
	v_mov_b64_e32 v[70:71], 0
	v_mov_b64_e32 v[72:73], 0
	v_mov_b64_e32 v[74:75], 0
	v_mov_b64_e32 v[76:77], 0
	v_mov_b64_e32 v[78:79], 0
	v_mov_b64_e32 v[80:81], 0
	v_mov_b64_e32 v[82:83], 0
	v_mov_b64_e32 v[84:85], 0
	v_mov_b64_e32 v[86:87], 0
	v_mov_b64_e32 v[88:89], 0
	v_mov_b64_e32 v[90:91], 0
	v_mov_b64_e32 v[92:93], 0
	v_mov_b64_e32 v[94:95], 0
	v_mov_b64_e32 v[96:97], 0
	v_mov_b64_e32 v[98:99], 0
	v_mov_b64_e32 v[100:101], 0
	v_mov_b64_e32 v[102:103], 0
	v_mov_b64_e32 v[104:105], 0
	v_mov_b64_e32 v[106:107], 0
	v_mov_b64_e32 v[108:109], 0
	v_mov_b64_e32 v[110:111], 0
	v_mov_b64_e32 v[112:113], 0
	v_mov_b64_e32 v[114:115], 0
	v_mov_b64_e32 v[116:117], 0
	v_mov_b64_e32 v[118:119], 0
	v_mov_b64_e32 v[120:121], 0
	v_mov_b64_e32 v[122:123], 0
	v_mov_b64_e32 v[124:125], 0
	v_mov_b64_e32 v[126:127], 0
	v_mov_b64_e32 v[128:129], 0
	s_addc_u32 s49, s23, 0
	s_mov_b32 s50, -2

; __device__ __forceinline__ unsigned cvt_pk_bf16(float lo, float hi) { unsigned r; asm volatile("v_cvt_pk_bf16_f32 %0, %1, %2" : "=v"(r) : "v"(lo), "v"(hi)); return r; }
; __device__ __forceinline__ float silu_f(float x) { return x * fast_rcp(1.0f + fast_exp2(-LOG2E * x)); }
;     __device__ __forceinline__ void operator()(const f32x4 (&acc)[2][2][4][2], const Unit& u, int wr, int wc, int fr, int fq) const {
;         const int row0 = u.pm * BM + wr * 64 + fr, col0 = u.pn * HALF + wc * 32 + 8 * fq;
;         float rrv[2][4];
; #pragma unroll
;         for (int ai = 0; ai < 2; ++ai)
; #pragma unroll
;             for (int m = 0; m < 4; ++m) rrv[ai][m] = rs[row0 + ai * HALF + m * 16];
; #pragma unroll
;         for (int ai = 0; ai < 2; ++ai)
; #pragma unroll
;             for (int m = 0; m < 4; ++m) {
;                 const float rr = rrv[ai][m];
;                 const f32x4 g0 = acc[ai][0][m][0] * rr, g1 = acc[ai][0][m][1] * rr, u0 = acc[ai][1][m][0] * rr, u1 = acc[ai][1][m][1] * rr;
;                 u32x4 w;
;                 w.x = cvt_pk_bf16(silu_f(g0[0]) * u0[0], silu_f(g0[1]) * u0[1]); w.y = cvt_pk_bf16(silu_f(g0[2]) * u0[2], silu_f(g0[3]) * u0[3]);
;                 w.z = cvt_pk_bf16(silu_f(g1[0]) * u1[0], silu_f(g1[1]) * u1[1]); w.w = cvt_pk_bf16(silu_f(g1[2]) * u1[2], silu_f(g1[3]) * u1[3]);
;                 *(u32x4*)(act + (size_t)(row0 + ai * HALF + m * 16) * DFF + col0) = w;
;             }
;     }
.LBB0_1553:
	v_lshl_add_u32 v162, s45, 8, v1
	v_ashrrev_i32_e32 v163, 31, v162
	v_lshl_add_u64 v[164:165], v[162:163], 2, s[8:9]
	v_mov_b32_e32 v166, v236
	v_mov_b32_e32 v142, v243
	v_or_b32_e32 v158, 16, v162
	v_ashrrev_i32_e32 v159, 31, v158
	v_lshl_add_u64 v[148:149], v[158:159], 2, s[8:9]
	v_mov_b32_e32 v160, v237
	v_or_b32_e32 v154, 32, v162
	v_ashrrev_i32_e32 v155, 31, v154
	v_or_b32_e32 v150, 48, v162
	v_lshl_add_u64 v[148:149], v[154:155], 2, s[8:9]
	v_ashrrev_i32_e32 v151, 31, v150
	v_mov_b32_e32 v156, v238
	v_mov_b32_e32 v146, v241
	v_lshl_add_u64 v[148:149], v[150:151], 2, s[8:9]
	v_mov_b32_e32 v152, v239
	v_mov_b32_e32 v144, v242
	s_movk_i32 s13, 0x1600
	v_mov_b32_e32 v148, v240
	v_lshl_or_b32 v164, s43, 7, v145
	v_ashrrev_i32_e32 v165, 31, v164
	v_add_u32_e32 v153, 0x90, v162
	v_add_u32_e32 v149, 0xb0, v162
	v_add_u32_e32 v155, 0x80, v162
	v_add_u32_e32 v151, 0xa0, v162
	s_cmp_eq_u32 s42, s40
	s_waitcnt vmcnt(8)
	v_pk_mul_f32 v[126:127], v[126:127], v[166:167] op_sel_hi:[1,0]
	v_pk_mul_f32 v[168:169], v[116:117], v[166:167] op_sel_hi:[1,0]
	v_pk_mul_f32 v[116:117], v[114:115], v[166:167] op_sel_hi:[1,0]
	v_mul_f32_e32 v114, 0xbfb8aa3b, v126
	v_mul_f32_e32 v115, 0xbfb8aa3b, v127
	v_exp_f32_e32 v114, v114
	v_exp_f32_e32 v115, v115
	v_pk_mul_f32 v[118:119], v[118:119], v[166:167] op_sel_hi:[1,0]
	v_pk_mul_f32 v[128:129], v[128:129], v[166:167] op_sel_hi:[1,0]
	v_add_f32_e32 v114, 1.0, v114
	v_add_f32_e32 v115, 1.0, v115
	v_rcp_f32_e32 v114, v114
	v_rcp_f32_e32 v115, v115
	v_pk_mul_f32 v[120:121], v[120:121], v[166:167] op_sel_hi:[1,0]
	v_pk_mul_f32 v[122:123], v[122:123], v[166:167] op_sel_hi:[1,0]
	v_mul_f32_e32 v114, v126, v114
	v_mul_f32_e32 v115, v127, v115
	v_mul_f32_e32 v114, v118, v114
	v_mul_f32_e32 v115, v119, v115
	v_cvt_pk_bf16_f32 v114, v114, v115
	v_mul_f32_e32 v115, 0xbfb8aa3b, v128
	v_mul_f32_e32 v118, 0xbfb8aa3b, v129
	v_exp_f32_e32 v115, v115
	v_exp_f32_e32 v118, v118
	v_pk_mul_f32 v[124:125], v[124:125], v[166:167] op_sel_hi:[1,0]
	v_pk_mul_f32 v[110:111], v[110:111], v[160:161] op_sel_hi:[1,0]
	v_add_f32_e32 v115, 1.0, v115
	v_add_f32_e32 v118, 1.0, v118
	v_rcp_f32_e32 v115, v115
	v_rcp_f32_e32 v118, v118
	v_pk_mul_f32 v[102:103], v[102:103], v[160:161] op_sel_hi:[1,0]
	v_pk_mul_f32 v[112:113], v[112:113], v[160:161] op_sel_hi:[1,0]
	v_mul_f32_e32 v115, v128, v115
	v_mul_f32_e32 v118, v129, v118
	v_mul_f32_e32 v115, v120, v115
	v_mul_f32_e32 v118, v121, v118
	v_cvt_pk_bf16_f32 v115, v115, v118
	v_mul_f32_e32 v118, 0xbfb8aa3b, v122
	v_exp_f32_e32 v118, v118
	v_lshlrev_b64 v[120:121], 1, v[164:165]
	v_pk_mul_f32 v[104:105], v[104:105], v[160:161] op_sel_hi:[1,0]
	v_pk_mul_f32 v[106:107], v[106:107], v[160:161] op_sel_hi:[1,0]
	v_add_f32_e32 v118, 1.0, v118
	v_rcp_f32_e32 v118, v118
	v_pk_mul_f32 v[98:99], v[98:99], v[160:161] op_sel_hi:[1,0]
	v_pk_mul_f32 v[108:109], v[108:109], v[160:161] op_sel_hi:[1,0]
	v_pk_mul_f32 v[100:101], v[100:101], v[160:161] op_sel_hi:[1,0]
	v_mul_f32_e32 v118, v122, v118
	v_mul_f32_e32 v116, v116, v118
	v_mul_f32_e32 v118, 0xbfb8aa3b, v123
	v_exp_f32_e32 v118, v118
	v_pk_mul_f32 v[94:95], v[94:95], v[156:157] op_sel_hi:[1,0]
	v_pk_mul_f32 v[86:87], v[86:87], v[156:157] op_sel_hi:[1,0]
	v_pk_mul_f32 v[96:97], v[96:97], v[156:157] op_sel_hi:[1,0]
	v_add_f32_e32 v118, 1.0, v118
	v_rcp_f32_e32 v118, v118
	v_pk_mul_f32 v[88:89], v[88:89], v[156:157] op_sel_hi:[1,0]
	v_pk_mul_f32 v[90:91], v[90:91], v[156:157] op_sel_hi:[1,0]
	v_pk_mul_f32 v[92:93], v[92:93], v[156:157] op_sel_hi:[1,0]
	v_mul_f32_e32 v118, v123, v118
	v_mul_f32_e32 v117, v117, v118
	v_cvt_pk_bf16_f32 v116, v116, v117
	v_mul_f32_e32 v117, 0xbfb8aa3b, v124
	v_mul_f32_e32 v118, 0xbfb8aa3b, v125
	v_exp_f32_e32 v117, v117
	v_exp_f32_e32 v118, v118
	v_pk_mul_f32 v[78:79], v[78:79], v[152:153] op_sel_hi:[1,0]
	v_pk_mul_f32 v[70:71], v[70:71], v[152:153] op_sel_hi:[1,0]
	v_add_f32_e32 v117, 1.0, v117
	v_add_f32_e32 v118, 1.0, v118
	v_rcp_f32_e32 v117, v117
	v_rcp_f32_e32 v118, v118
	v_pk_mul_f32 v[80:81], v[80:81], v[152:153] op_sel_hi:[1,0]
	v_pk_mul_f32 v[72:73], v[72:73], v[152:153] op_sel_hi:[1,0]
	v_mul_f32_e32 v117, v124, v117
	v_mul_f32_e32 v118, v125, v118
	v_mul_f32_e32 v117, v168, v117
	v_mul_f32_e32 v118, v169, v118
	v_cvt_pk_bf16_f32 v117, v117, v118
	v_mov_b64_e32 v[118:119], s[6:7]
	v_mad_i64_i32 v[122:123], s[20:21], v162, s13, v[118:119]
	v_lshl_add_u64 v[122:123], v[122:123], 0, v[120:121]
	global_store_dwordx4 v[122:123], v[114:117], off
	v_pk_mul_f32 v[74:75], v[74:75], v[152:153] op_sel_hi:[1,0]
	v_pk_mul_f32 v[76:77], v[76:77], v[152:153] op_sel_hi:[1,0]
	v_mul_f32_e32 v114, 0xbfb8aa3b, v110
	v_exp_f32_e32 v114, v114
	v_pk_mul_f32 v[62:63], v[62:63], v[148:149] op_sel_hi:[1,0]
	v_pk_mul_f32 v[54:55], v[54:55], v[148:149] op_sel_hi:[1,0]
	v_pk_mul_f32 v[64:65], v[64:65], v[148:149] op_sel_hi:[1,0]
	v_add_f32_e32 v114, 1.0, v114
	v_rcp_f32_e32 v114, v114
	v_pk_mul_f32 v[56:57], v[56:57], v[148:149] op_sel_hi:[1,0]
	v_pk_mul_f32 v[58:59], v[58:59], v[148:149] op_sel_hi:[1,0]
	v_pk_mul_f32 v[60:61], v[60:61], v[148:149] op_sel_hi:[1,0]
	v_mul_f32_e32 v110, v110, v114
	v_mul_f32_e32 v102, v102, v110
	v_mul_f32_e32 v110, 0xbfb8aa3b, v111
	v_exp_f32_e32 v110, v110
	v_pk_mul_f32 v[46:47], v[46:47], v[146:147] op_sel_hi:[1,0]
	v_pk_mul_f32 v[38:39], v[38:39], v[146:147] op_sel_hi:[1,0]
	v_pk_mul_f32 v[48:49], v[48:49], v[146:147] op_sel_hi:[1,0]
	v_add_f32_e32 v110, 1.0, v110
	v_rcp_f32_e32 v110, v110
	v_pk_mul_f32 v[40:41], v[40:41], v[146:147] op_sel_hi:[1,0]
	v_pk_mul_f32 v[42:43], v[42:43], v[146:147] op_sel_hi:[1,0]
	v_pk_mul_f32 v[44:45], v[44:45], v[146:147] op_sel_hi:[1,0]
	v_mul_f32_e32 v110, v111, v110
; __device__ __forceinline__ unsigned cvt_pk_bf16(float lo, float hi) { unsigned r; asm volatile("v_cvt_pk_bf16_f32 %0, %1, %2" : "=v"(r) : "v"(lo), "v"(hi)); return r; }
; __device__ __forceinline__ float silu_f(float x) { return x * fast_rcp(1.0f + fast_exp2(-LOG2E * x)); }
;     __device__ __forceinline__ void operator()(const f32x4 (&acc)[2][2][4][2], const Unit& u, int wr, int wc, int fr, int fq) const {
;         const int row0 = u.pm * BM + wr * 64 + fr, col0 = u.pn * HALF + wc * 32 + 8 * fq;
;         float rrv[2][4];
; #pragma unroll
;         for (int ai = 0; ai < 2; ++ai)
; #pragma unroll
;             for (int m = 0; m < 4; ++m) rrv[ai][m] = rs[row0 + ai * HALF + m * 16];
; #pragma unroll
;         for (int ai = 0; ai < 2; ++ai)
; #pragma unroll
;             for (int m = 0; m < 4; ++m) {
;                 const float rr = rrv[ai][m];
;                 const f32x4 g0 = acc[ai][0][m][0] * rr, g1 = acc[ai][0][m][1] * rr, u0 = acc[ai][1][m][0] * rr, u1 = acc[ai][1][m][1] * rr;
;                 u32x4 w;
;                 w.x = cvt_pk_bf16(silu_f(g0[0]) * u0[0], silu_f(g0[1]) * u0[1]); w.y = cvt_pk_bf16(silu_f(g0[2]) * u0[2], silu_f(g0[3]) * u0[3]);
;                 w.z = cvt_pk_bf16(silu_f(g1[0]) * u1[0], silu_f(g1[1]) * u1[1]); w.w = cvt_pk_bf16(silu_f(g1[2]) * u1[2], silu_f(g1[3]) * u1[3]);
;                 *(u32x4*)(act + (size_t)(row0 + ai * HALF + m * 16) * DFF + col0) = w;
;             }
;     }
	v_mul_f32_e32 v103, v103, v110
	v_cvt_pk_bf16_f32 v102, v102, v103
	v_mul_f32_e32 v103, 0xbfb8aa3b, v112
	v_exp_f32_e32 v103, v103
	v_pk_mul_f32 v[30:31], v[30:31], v[144:145] op_sel_hi:[1,0]
	v_pk_mul_f32 v[22:23], v[22:23], v[144:145] op_sel_hi:[1,0]
	v_pk_mul_f32 v[32:33], v[32:33], v[144:145] op_sel_hi:[1,0]
	v_add_f32_e32 v103, 1.0, v103
	v_rcp_f32_e32 v103, v103
	v_pk_mul_f32 v[24:25], v[24:25], v[144:145] op_sel_hi:[1,0]
	v_pk_mul_f32 v[26:27], v[26:27], v[144:145] op_sel_hi:[1,0]
	v_pk_mul_f32 v[28:29], v[28:29], v[144:145] op_sel_hi:[1,0]
	v_mul_f32_e32 v103, v112, v103
	v_mul_f32_e32 v103, v104, v103
	v_mul_f32_e32 v104, 0xbfb8aa3b, v113
	v_exp_f32_e32 v104, v104
	v_pk_mul_f32 v[14:15], v[14:15], v[142:143] op_sel_hi:[1,0]
	v_pk_mul_f32 v[6:7], v[6:7], v[142:143] op_sel_hi:[1,0]
	v_pk_mul_f32 v[16:17], v[16:17], v[142:143] op_sel_hi:[1,0]
	v_add_f32_e32 v104, 1.0, v104
	v_rcp_f32_e32 v104, v104
	v_pk_mul_f32 v[8:9], v[8:9], v[142:143] op_sel_hi:[1,0]
	v_pk_mul_f32 v[10:11], v[10:11], v[142:143] op_sel_hi:[1,0]
	v_pk_mul_f32 v[12:13], v[12:13], v[142:143] op_sel_hi:[1,0]
	v_mul_f32_e32 v104, v113, v104
	v_mul_f32_e32 v104, v105, v104
	v_cvt_pk_bf16_f32 v103, v103, v104
	v_mul_f32_e32 v104, 0xbfb8aa3b, v106
	v_exp_f32_e32 v104, v104
	s_nop 0
	v_add_f32_e32 v104, 1.0, v104
	v_rcp_f32_e32 v104, v104
	s_nop 0
	v_mul_f32_e32 v104, v106, v104
	v_mul_f32_e32 v98, v98, v104
	v_mul_f32_e32 v104, 0xbfb8aa3b, v107
	v_exp_f32_e32 v104, v104
	s_nop 0
	v_add_f32_e32 v104, 1.0, v104
	v_rcp_f32_e32 v104, v104
	s_nop 0
	v_mul_f32_e32 v104, v107, v104
	v_mul_f32_e32 v99, v99, v104
	v_cvt_pk_bf16_f32 v104, v98, v99
	v_mul_f32_e32 v98, 0xbfb8aa3b, v108
	v_mul_f32_e32 v99, 0xbfb8aa3b, v109
	v_exp_f32_e32 v98, v98
	v_exp_f32_e32 v99, v99
	v_add_f32_e32 v98, 1.0, v98
	v_add_f32_e32 v99, 1.0, v99
	v_rcp_f32_e32 v98, v98
	v_rcp_f32_e32 v99, v99
	v_mul_f32_e32 v98, v108, v98
	v_mul_f32_e32 v99, v109, v99
	v_mul_f32_e32 v98, v100, v98
	v_mul_f32_e32 v99, v101, v99
	v_cvt_pk_bf16_f32 v105, v98, v99
	v_mad_i64_i32 v[98:99], s[20:21], v158, s13, v[118:119]
	v_lshl_add_u64 v[98:99], v[98:99], 0, v[120:121]
	global_store_dwordx4 v[98:99], v[102:105], off
	v_pk_mul_f32 v[98:99], v[84:85], v[156:157] op_sel_hi:[1,0]
	v_pk_mul_f32 v[84:85], v[82:83], v[156:157] op_sel_hi:[1,0]
	v_mul_f32_e32 v82, 0xbfb8aa3b, v94
	v_mul_f32_e32 v83, 0xbfb8aa3b, v95
	v_exp_f32_e32 v82, v82
	v_exp_f32_e32 v83, v83
	v_add_f32_e32 v82, 1.0, v82
	v_add_f32_e32 v83, 1.0, v83
	v_rcp_f32_e32 v82, v82
	v_rcp_f32_e32 v83, v83
	v_mul_f32_e32 v82, v94, v82
	v_mul_f32_e32 v83, v95, v83
	v_mul_f32_e32 v82, v86, v82
	v_mul_f32_e32 v83, v87, v83
	v_cvt_pk_bf16_f32 v82, v82, v83
	v_mul_f32_e32 v83, 0xbfb8aa3b, v96
	v_mul_f32_e32 v86, 0xbfb8aa3b, v97
	v_exp_f32_e32 v83, v83
	v_exp_f32_e32 v86, v86
	v_add_f32_e32 v83, 1.0, v83
	v_add_f32_e32 v86, 1.0, v86
	v_rcp_f32_e32 v83, v83
	v_rcp_f32_e32 v86, v86
	v_mul_f32_e32 v83, v96, v83
	v_mul_f32_e32 v86, v97, v86
	v_mul_f32_e32 v83, v88, v83
	v_mul_f32_e32 v86, v89, v86
	v_cvt_pk_bf16_f32 v83, v83, v86
	v_mul_f32_e32 v86, 0xbfb8aa3b, v90
	v_exp_f32_e32 v86, v86
	s_nop 0
	v_add_f32_e32 v86, 1.0, v86
	v_rcp_f32_e32 v86, v86
	s_nop 0
	v_mul_f32_e32 v86, v90, v86
	v_mul_f32_e32 v84, v84, v86
	v_mul_f32_e32 v86, 0xbfb8aa3b, v91
	v_exp_f32_e32 v86, v86
	s_nop 0
	v_add_f32_e32 v86, 1.0, v86
	v_rcp_f32_e32 v86, v86
	s_nop 0
	v_mul_f32_e32 v86, v91, v86
	v_mul_f32_e32 v85, v85, v86
	v_cvt_pk_bf16_f32 v84, v84, v85
	v_mul_f32_e32 v85, 0xbfb8aa3b, v92
	v_mul_f32_e32 v86, 0xbfb8aa3b, v93
	v_exp_f32_e32 v85, v85
	v_exp_f32_e32 v86, v86
	v_add_f32_e32 v85, 1.0, v85
	v_add_f32_e32 v86, 1.0, v86
	v_rcp_f32_e32 v85, v85
	v_rcp_f32_e32 v86, v86
	v_mul_f32_e32 v85, v92, v85
	v_mul_f32_e32 v86, v93, v86
	v_mul_f32_e32 v85, v98, v85
	v_mul_f32_e32 v86, v99, v86
	v_cvt_pk_bf16_f32 v85, v85, v86
	v_mad_i64_i32 v[86:87], s[20:21], v154, s13, v[118:119]
	v_lshl_add_u64 v[86:87], v[86:87], 0, v[120:121]
	global_store_dwordx4 v[86:87], v[82:85], off
	s_nop 1
	v_pk_mul_f32 v[82:83], v[68:69], v[152:153] op_sel_hi:[1,0]
	v_pk_mul_f32 v[68:69], v[66:67], v[152:153] op_sel_hi:[1,0]
	v_mul_f32_e32 v66, 0xbfb8aa3b, v78
	v_mul_f32_e32 v67, 0xbfb8aa3b, v79
	v_exp_f32_e32 v66, v66
	v_exp_f32_e32 v67, v67
	v_add_f32_e32 v66, 1.0, v66
	v_add_f32_e32 v67, 1.0, v67
	v_rcp_f32_e32 v66, v66
	v_rcp_f32_e32 v67, v67
	v_mul_f32_e32 v66, v78, v66
	v_mul_f32_e32 v67, v79, v67
	v_mul_f32_e32 v66, v70, v66
	v_mul_f32_e32 v67, v71, v67
	v_cvt_pk_bf16_f32 v66, v66, v67
	v_mul_f32_e32 v67, 0xbfb8aa3b, v80
	v_mul_f32_e32 v70, 0xbfb8aa3b, v81
	v_exp_f32_e32 v67, v67
	v_exp_f32_e32 v70, v70
	v_add_f32_e32 v67, 1.0, v67
	v_add_f32_e32 v70, 1.0, v70
	v_rcp_f32_e32 v67, v67
	v_rcp_f32_e32 v70, v70
	v_mul_f32_e32 v67, v80, v67
	v_mul_f32_e32 v70, v81, v70
	v_mul_f32_e32 v67, v72, v67
	v_mul_f32_e32 v70, v73, v70
	v_cvt_pk_bf16_f32 v67, v67, v70
	v_mul_f32_e32 v70, 0xbfb8aa3b, v74
	v_exp_f32_e32 v70, v70
	s_nop 0
	v_add_f32_e32 v70, 1.0, v70
	v_rcp_f32_e32 v70, v70
	s_nop 0
	v_mul_f32_e32 v70, v74, v70
	v_mul_f32_e32 v68, v68, v70
	v_mul_f32_e32 v70, 0xbfb8aa3b, v75
	v_exp_f32_e32 v70, v70
	s_nop 0
	v_add_f32_e32 v70, 1.0, v70
	v_rcp_f32_e32 v70, v70
	s_nop 0
	v_mul_f32_e32 v70, v75, v70
	v_mul_f32_e32 v69, v69, v70
	v_cvt_pk_bf16_f32 v68, v68, v69
	v_mul_f32_e32 v69, 0xbfb8aa3b, v76
	v_mul_f32_e32 v70, 0xbfb8aa3b, v77
	v_exp_f32_e32 v69, v69
	v_exp_f32_e32 v70, v70
	v_add_f32_e32 v69, 1.0, v69
	v_add_f32_e32 v70, 1.0, v70
	v_rcp_f32_e32 v69, v69
	v_rcp_f32_e32 v70, v70
	v_mul_f32_e32 v69, v76, v69
	v_mul_f32_e32 v70, v77, v70
	v_mul_f32_e32 v69, v82, v69
	v_mul_f32_e32 v70, v83, v70
	v_cvt_pk_bf16_f32 v69, v69, v70
; __device__ __forceinline__ unsigned cvt_pk_bf16(float lo, float hi) { unsigned r; asm volatile("v_cvt_pk_bf16_f32 %0, %1, %2" : "=v"(r) : "v"(lo), "v"(hi)); return r; }
; __device__ __forceinline__ float silu_f(float x) { return x * fast_rcp(1.0f + fast_exp2(-LOG2E * x)); }
;     __device__ __forceinline__ void operator()(const f32x4 (&acc)[2][2][4][2], const Unit& u, int wr, int wc, int fr, int fq) const {
;         const int row0 = u.pm * BM + wr * 64 + fr, col0 = u.pn * HALF + wc * 32 + 8 * fq;
;         float rrv[2][4];
; #pragma unroll
;         for (int ai = 0; ai < 2; ++ai)
; #pragma unroll
;             for (int m = 0; m < 4; ++m) rrv[ai][m] = rs[row0 + ai * HALF + m * 16];
; #pragma unroll
;         for (int ai = 0; ai < 2; ++ai)
; #pragma unroll
;             for (int m = 0; m < 4; ++m) {
;                 const float rr = rrv[ai][m];
;                 const f32x4 g0 = acc[ai][0][m][0] * rr, g1 = acc[ai][0][m][1] * rr, u0 = acc[ai][1][m][0] * rr, u1 = acc[ai][1][m][1] * rr;
;                 u32x4 w;
;                 w.x = cvt_pk_bf16(silu_f(g0[0]) * u0[0], silu_f(g0[1]) * u0[1]); w.y = cvt_pk_bf16(silu_f(g0[2]) * u0[2], silu_f(g0[3]) * u0[3]);
;                 w.z = cvt_pk_bf16(silu_f(g1[0]) * u1[0], silu_f(g1[1]) * u1[1]); w.w = cvt_pk_bf16(silu_f(g1[2]) * u1[2], silu_f(g1[3]) * u1[3]);
;                 *(u32x4*)(act + (size_t)(row0 + ai * HALF + m * 16) * DFF + col0) = w;
;             }
;     }
	v_mad_i64_i32 v[70:71], s[20:21], v150, s13, v[118:119]
	v_lshl_add_u64 v[70:71], v[70:71], 0, v[120:121]
	global_store_dwordx4 v[70:71], v[66:69], off
	s_nop 1
	v_pk_mul_f32 v[66:67], v[52:53], v[148:149] op_sel_hi:[1,0]
	v_pk_mul_f32 v[52:53], v[50:51], v[148:149] op_sel_hi:[1,0]
	v_mul_f32_e32 v50, 0xbfb8aa3b, v62
	v_mul_f32_e32 v51, 0xbfb8aa3b, v63
	v_exp_f32_e32 v50, v50
	v_exp_f32_e32 v51, v51
	v_add_f32_e32 v50, 1.0, v50
	v_add_f32_e32 v51, 1.0, v51
	v_rcp_f32_e32 v50, v50
	v_rcp_f32_e32 v51, v51
	v_mul_f32_e32 v50, v62, v50
	v_mul_f32_e32 v51, v63, v51
	v_mul_f32_e32 v50, v54, v50
	v_mul_f32_e32 v51, v55, v51
	v_cvt_pk_bf16_f32 v50, v50, v51
	v_mul_f32_e32 v51, 0xbfb8aa3b, v64
	v_mul_f32_e32 v54, 0xbfb8aa3b, v65
	v_exp_f32_e32 v51, v51
	v_exp_f32_e32 v54, v54
	v_add_f32_e32 v51, 1.0, v51
	v_add_f32_e32 v54, 1.0, v54
	v_rcp_f32_e32 v51, v51
	v_rcp_f32_e32 v54, v54
	v_mul_f32_e32 v51, v64, v51
	v_mul_f32_e32 v54, v65, v54
	v_mul_f32_e32 v51, v56, v51
	v_mul_f32_e32 v54, v57, v54
	v_cvt_pk_bf16_f32 v51, v51, v54
	v_mul_f32_e32 v54, 0xbfb8aa3b, v58
	v_exp_f32_e32 v54, v54
	s_nop 0
	v_add_f32_e32 v54, 1.0, v54
	v_rcp_f32_e32 v54, v54
	s_nop 0
	v_mul_f32_e32 v54, v58, v54
	v_mul_f32_e32 v52, v52, v54
	v_mul_f32_e32 v54, 0xbfb8aa3b, v59
	v_exp_f32_e32 v54, v54
	s_nop 0
	v_add_f32_e32 v54, 1.0, v54
	v_rcp_f32_e32 v54, v54
	s_nop 0
	v_mul_f32_e32 v54, v59, v54
	v_mul_f32_e32 v53, v53, v54
	v_cvt_pk_bf16_f32 v52, v52, v53
	v_mul_f32_e32 v53, 0xbfb8aa3b, v60
	v_mul_f32_e32 v54, 0xbfb8aa3b, v61
	v_exp_f32_e32 v53, v53
	v_exp_f32_e32 v54, v54
	v_add_f32_e32 v53, 1.0, v53
	v_add_f32_e32 v54, 1.0, v54
	v_rcp_f32_e32 v53, v53
	v_rcp_f32_e32 v54, v54
	v_mul_f32_e32 v53, v60, v53
	v_mul_f32_e32 v54, v61, v54
	v_mul_f32_e32 v53, v66, v53
	v_mul_f32_e32 v54, v67, v54
	v_cvt_pk_bf16_f32 v53, v53, v54
	v_mad_i64_i32 v[54:55], s[20:21], v155, s13, v[118:119]
	v_lshl_add_u64 v[54:55], v[54:55], 0, v[120:121]
	global_store_dwordx4 v[54:55], v[50:53], off
	s_nop 1
	v_pk_mul_f32 v[50:51], v[36:37], v[146:147] op_sel_hi:[1,0]
	v_pk_mul_f32 v[36:37], v[34:35], v[146:147] op_sel_hi:[1,0]
	v_mul_f32_e32 v34, 0xbfb8aa3b, v46
	v_mul_f32_e32 v35, 0xbfb8aa3b, v47
	v_exp_f32_e32 v34, v34
	v_exp_f32_e32 v35, v35
	v_add_f32_e32 v34, 1.0, v34
	v_add_f32_e32 v35, 1.0, v35
	v_rcp_f32_e32 v34, v34
	v_rcp_f32_e32 v35, v35
	v_mul_f32_e32 v34, v46, v34
	v_mul_f32_e32 v35, v47, v35
	v_mul_f32_e32 v34, v38, v34
	v_mul_f32_e32 v35, v39, v35
	v_cvt_pk_bf16_f32 v34, v34, v35
	v_mul_f32_e32 v35, 0xbfb8aa3b, v48
	v_mul_f32_e32 v38, 0xbfb8aa3b, v49
	v_exp_f32_e32 v35, v35
	v_exp_f32_e32 v38, v38
	v_add_f32_e32 v35, 1.0, v35
	v_add_f32_e32 v38, 1.0, v38
	v_rcp_f32_e32 v35, v35
	v_rcp_f32_e32 v38, v38
	v_mul_f32_e32 v35, v48, v35
	v_mul_f32_e32 v38, v49, v38
	v_mul_f32_e32 v35, v40, v35
	v_mul_f32_e32 v38, v41, v38
	v_cvt_pk_bf16_f32 v35, v35, v38
	v_mul_f32_e32 v38, 0xbfb8aa3b, v42
	v_exp_f32_e32 v38, v38
	s_nop 0
	v_add_f32_e32 v38, 1.0, v38
	v_rcp_f32_e32 v38, v38
	s_nop 0
	v_mul_f32_e32 v38, v42, v38
	v_mul_f32_e32 v36, v36, v38
	v_mul_f32_e32 v38, 0xbfb8aa3b, v43
	v_exp_f32_e32 v38, v38
	s_nop 0
	v_add_f32_e32 v38, 1.0, v38
	v_rcp_f32_e32 v38, v38
	s_nop 0
	v_mul_f32_e32 v38, v43, v38
	v_mul_f32_e32 v37, v37, v38
	v_cvt_pk_bf16_f32 v36, v36, v37
	v_mul_f32_e32 v37, 0xbfb8aa3b, v44
	v_mul_f32_e32 v38, 0xbfb8aa3b, v45
	v_exp_f32_e32 v37, v37
	v_exp_f32_e32 v38, v38
	v_add_f32_e32 v37, 1.0, v37
	v_add_f32_e32 v38, 1.0, v38
	v_rcp_f32_e32 v37, v37
	v_rcp_f32_e32 v38, v38
	v_mul_f32_e32 v37, v44, v37
	v_mul_f32_e32 v38, v45, v38
	v_mul_f32_e32 v37, v50, v37
	v_mul_f32_e32 v38, v51, v38
	v_cvt_pk_bf16_f32 v37, v37, v38
	v_mad_i64_i32 v[38:39], s[20:21], v153, s13, v[118:119]
	v_lshl_add_u64 v[38:39], v[38:39], 0, v[120:121]
; __device__ __forceinline__ unsigned cvt_pk_bf16(float lo, float hi) { unsigned r; asm volatile("v_cvt_pk_bf16_f32 %0, %1, %2" : "=v"(r) : "v"(lo), "v"(hi)); return r; }
; __device__ __forceinline__ float silu_f(float x) { return x * fast_rcp(1.0f + fast_exp2(-LOG2E * x)); }
;     __device__ __forceinline__ void operator()(const f32x4 (&acc)[2][2][4][2], const Unit& u, int wr, int wc, int fr, int fq) const {
;         const int row0 = u.pm * BM + wr * 64 + fr, col0 = u.pn * HALF + wc * 32 + 8 * fq;
;         float rrv[2][4];
; #pragma unroll
;         for (int ai = 0; ai < 2; ++ai)
; #pragma unroll
;             for (int m = 0; m < 4; ++m) rrv[ai][m] = rs[row0 + ai * HALF + m * 16];
; #pragma unroll
;         for (int ai = 0; ai < 2; ++ai)
; #pragma unroll
;             for (int m = 0; m < 4; ++m) {
;                 const float rr = rrv[ai][m];
;                 const f32x4 g0 = acc[ai][0][m][0] * rr, g1 = acc[ai][0][m][1] * rr, u0 = acc[ai][1][m][0] * rr, u1 = acc[ai][1][m][1] * rr;
;                 u32x4 w;
;                 w.x = cvt_pk_bf16(silu_f(g0[0]) * u0[0], silu_f(g0[1]) * u0[1]); w.y = cvt_pk_bf16(silu_f(g0[2]) * u0[2], silu_f(g0[3]) * u0[3]);
;                 w.z = cvt_pk_bf16(silu_f(g1[0]) * u1[0], silu_f(g1[1]) * u1[1]); w.w = cvt_pk_bf16(silu_f(g1[2]) * u1[2], silu_f(g1[3]) * u1[3]);
;                 *(u32x4*)(act + (size_t)(row0 + ai * HALF + m * 16) * DFF + col0) = w;
;             }
;     }
	global_store_dwordx4 v[38:39], v[34:37], off
	s_nop 1
	v_pk_mul_f32 v[34:35], v[20:21], v[144:145] op_sel_hi:[1,0]
	v_pk_mul_f32 v[20:21], v[18:19], v[144:145] op_sel_hi:[1,0]
	v_mul_f32_e32 v18, 0xbfb8aa3b, v30
	v_mul_f32_e32 v19, 0xbfb8aa3b, v31
	v_exp_f32_e32 v18, v18
	v_exp_f32_e32 v19, v19
	v_add_f32_e32 v18, 1.0, v18
	v_add_f32_e32 v19, 1.0, v19
	v_rcp_f32_e32 v18, v18
	v_rcp_f32_e32 v19, v19
	v_mul_f32_e32 v18, v30, v18
	v_mul_f32_e32 v19, v31, v19
	v_mul_f32_e32 v18, v22, v18
	v_mul_f32_e32 v19, v23, v19
	v_cvt_pk_bf16_f32 v18, v18, v19
	v_mul_f32_e32 v19, 0xbfb8aa3b, v32
	v_mul_f32_e32 v22, 0xbfb8aa3b, v33
	v_exp_f32_e32 v19, v19
	v_exp_f32_e32 v22, v22
	v_add_f32_e32 v19, 1.0, v19
	v_add_f32_e32 v22, 1.0, v22
	v_rcp_f32_e32 v19, v19
	v_rcp_f32_e32 v22, v22
	v_mul_f32_e32 v19, v32, v19
	v_mul_f32_e32 v22, v33, v22
	v_mul_f32_e32 v19, v24, v19
	v_mul_f32_e32 v22, v25, v22
	v_cvt_pk_bf16_f32 v19, v19, v22
	v_mul_f32_e32 v22, 0xbfb8aa3b, v26
	v_exp_f32_e32 v22, v22
	s_nop 0
	v_add_f32_e32 v22, 1.0, v22
	v_rcp_f32_e32 v22, v22
	s_nop 0
	v_mul_f32_e32 v22, v26, v22
	v_mul_f32_e32 v20, v20, v22
	v_mul_f32_e32 v22, 0xbfb8aa3b, v27
	v_exp_f32_e32 v22, v22
	s_nop 0
	v_add_f32_e32 v22, 1.0, v22
	v_rcp_f32_e32 v22, v22
	s_nop 0
	v_mul_f32_e32 v22, v27, v22
	v_mul_f32_e32 v21, v21, v22
	v_cvt_pk_bf16_f32 v20, v20, v21
	v_mul_f32_e32 v21, 0xbfb8aa3b, v28
	v_mul_f32_e32 v22, 0xbfb8aa3b, v29
	v_exp_f32_e32 v21, v21
	v_exp_f32_e32 v22, v22
	v_add_f32_e32 v21, 1.0, v21
	v_add_f32_e32 v22, 1.0, v22
	v_rcp_f32_e32 v21, v21
	v_rcp_f32_e32 v22, v22
	v_mul_f32_e32 v21, v28, v21
	v_mul_f32_e32 v22, v29, v22
	v_mul_f32_e32 v21, v34, v21
	v_mul_f32_e32 v22, v35, v22
	v_cvt_pk_bf16_f32 v21, v21, v22
	v_mad_i64_i32 v[22:23], s[20:21], v151, s13, v[118:119]
	v_lshl_add_u64 v[22:23], v[22:23], 0, v[120:121]
	global_store_dwordx4 v[22:23], v[18:21], off
	s_nop 1
	v_pk_mul_f32 v[18:19], v[4:5], v[142:143] op_sel_hi:[1,0]
	v_pk_mul_f32 v[4:5], v[2:3], v[142:143] op_sel_hi:[1,0]
	v_mul_f32_e32 v2, 0xbfb8aa3b, v14
	v_mul_f32_e32 v3, 0xbfb8aa3b, v15
	v_exp_f32_e32 v2, v2
	v_exp_f32_e32 v3, v3
	v_add_f32_e32 v2, 1.0, v2
	v_add_f32_e32 v3, 1.0, v3
	v_rcp_f32_e32 v2, v2
	v_rcp_f32_e32 v3, v3
	v_mul_f32_e32 v2, v14, v2
	v_mul_f32_e32 v3, v15, v3
	v_mul_f32_e32 v2, v6, v2
	v_mul_f32_e32 v3, v7, v3
	v_cvt_pk_bf16_f32 v2, v2, v3
	v_mul_f32_e32 v3, 0xbfb8aa3b, v16
	v_mul_f32_e32 v6, 0xbfb8aa3b, v17
	v_exp_f32_e32 v3, v3
	v_exp_f32_e32 v6, v6
	v_add_f32_e32 v3, 1.0, v3
	v_add_f32_e32 v6, 1.0, v6
	v_rcp_f32_e32 v3, v3
	v_rcp_f32_e32 v6, v6
	v_mul_f32_e32 v3, v16, v3
	v_mul_f32_e32 v6, v17, v6
	v_mul_f32_e32 v3, v8, v3
	v_mul_f32_e32 v6, v9, v6
	v_cvt_pk_bf16_f32 v3, v3, v6
	v_mul_f32_e32 v6, 0xbfb8aa3b, v10
	v_exp_f32_e32 v6, v6
	s_nop 0
	v_add_f32_e32 v6, 1.0, v6
	v_rcp_f32_e32 v6, v6
	s_nop 0
	v_mul_f32_e32 v6, v10, v6
	v_mul_f32_e32 v4, v4, v6
	v_mul_f32_e32 v6, 0xbfb8aa3b, v11
	v_exp_f32_e32 v6, v6
	s_nop 0
	v_add_f32_e32 v6, 1.0, v6
	v_rcp_f32_e32 v6, v6
	s_nop 0
	v_mul_f32_e32 v6, v11, v6
	v_mul_f32_e32 v5, v5, v6
	v_cvt_pk_bf16_f32 v4, v4, v5
	v_mul_f32_e32 v5, 0xbfb8aa3b, v12
	v_mul_f32_e32 v6, 0xbfb8aa3b, v13
	v_exp_f32_e32 v5, v5
	v_exp_f32_e32 v6, v6
	v_add_f32_e32 v5, 1.0, v5
	v_add_f32_e32 v6, 1.0, v6
	v_rcp_f32_e32 v5, v5
	v_rcp_f32_e32 v6, v6
	v_mul_f32_e32 v5, v12, v5
	v_mul_f32_e32 v6, v13, v6
	v_mul_f32_e32 v5, v18, v5
	v_mul_f32_e32 v6, v19, v6
	v_cvt_pk_bf16_f32 v5, v5, v6
	v_mad_i64_i32 v[6:7], s[20:21], v149, s13, v[118:119]
	v_lshl_add_u64 v[6:7], v[6:7], 0, v[120:121]
	s_mov_b64 s[20:21], -1
	global_store_dwordx4 v[6:7], v[2:5], off
	s_cbranch_scc1 .LBB0_1546
	s_andn2_b64 vcc, exec, s[4:5]
	s_cbranch_vccnz .LBB0_1545
	s_barrier
	s_branch .LBB0_1545
